# strategy 9 loop-edge edits: out-proj K loop step-kind tests and readfirstlane moved in front of the barrier (first post-barrier instruction is the branch into the DMA issue)
# baseline (speedup 1.0000x reference)
.LBB0_74:
	s_and_b32 s10, s8, 0xffffe00
	v_readlane_b32 s13, v253, 45
	s_or_b32 s10, s13, s10
	s_and_b32 s12, s9, 56
	s_add_i32 s10, s10, s12
	s_lshl_b32 s10, s10, 4
	v_mov_b32_e32 v8, v151
	s_ashr_i32 s11, s10, 31
	s_lshl_b64 s[40:41], s[10:11], 1
	v_bfe_u32 v12, v8, 4, 2
	s_and_b32 s10, s7, 7
	v_and_b32_e32 v9, 63, v8
	v_ashrrev_i32_e32 v11, 6, v8
	v_xor_b32_e32 v0, v12, v8
	s_lshl_b32 s11, s10, 18
	s_lshl_b32 s10, s9, 3
	v_lshl_or_b32 v3, v11, 8, v9
	v_lshlrev_b32_e32 v0, 3, v0
	s_and_b32 s10, s10, 0xfffffe00
	s_or_b32 s12, s12, s13
	v_lshlrev_b32_e32 v2, 7, v3
	v_and_b32_e32 v13, 56, v0
	s_movk_i32 s42, 0x9c00
	s_or_b32 s10, s12, s10
	v_and_or_b32 v0, v2, s42, v13
	v_or_b32_e32 v2, 64, v3
	s_ashr_i32 s12, s10, 3
	v_lshrrev_b32_e32 v4, 4, v2
	s_ashr_i32 s13, s12, 31
	v_xor_b32_e32 v4, v4, v8
	v_or_b32_e32 v3, 0xc0, v3
	s_and_b32 s10, s9, 7
	s_lshl_b64 s[28:29], s[12:13], 17
	s_lshl_b64 s[38:39], s[12:13], 18
	v_lshlrev_b32_e32 v14, 7, v2
	v_lshlrev_b32_e32 v2, 3, v4
	v_lshrrev_b32_e32 v4, 4, v3
	s_add_u32 s12, s94, s38
	v_xor_b32_e32 v4, v4, v8
	v_lshlrev_b32_e32 v122, 12, v11
	s_addc_u32 s13, s95, s39
	s_lshl_b32 s14, s10, 18
	v_lshlrev_b32_e32 v16, 7, v3
	v_lshlrev_b32_e32 v3, 3, v4
	v_lshlrev_b64 v[4:5], 1, v[0:1]
	v_readfirstlane_b32 s16, v122
	v_add_u32_e32 v123, 0x4000, v122
	s_add_u32 s14, s5, s14
	v_lshl_add_u64 v[6:7], s[12:13], 0, v[4:5]
	s_mov_b32 m0, s16
	v_readfirstlane_b32 s16, v123
	s_addc_u32 s15, s6, 0
	v_and_b32_e32 v15, 56, v2
	s_mov_b64 s[48:49], s[12:13]
	s_mov_b64 s[100:101], s[14:15]
	v_and_b32_e32 v250, 63, v151
	v_lshrrev_b32_e32 v251, 4, v250
	v_and_b32_e32 v185, 7, v250
	v_xor_b32_e32 v185, v185, v251
	v_lshlrev_b32_e32 v185, 4, v185
	v_lshrrev_b32_e32 v251, 3, v250
	v_lshl_or_b32 v185, v251, 11, v185
	v_lshrrev_b32_e32 v251, 6, v151
	v_lshl_add_u32 v185, v251, 16, v185
	v_add_u32_e32 v185, 0x80, v185
	v_xor_b32_e32 v188, 64, v185
	v_add_u32_e32 v188, 0x4000, v188
	v_add_u32_e32 v193, 0x8000, v185
	v_add_u32_e32 v194, 0x8000, v188
	s_barrier
	global_load_lds_dwordx4 v[6:7], off
	s_mov_b32 m0, s16
	s_movk_i32 s16, 0xbc00
	v_or_b32_e32 v2, 0x4000, v0
	v_lshl_add_u64 v[4:5], s[14:15], 0, v[4:5]
	v_and_or_b32 v0, v14, s16, v15
	global_load_lds_dwordx4 v[4:5], off
	v_lshlrev_b64 v[4:5], 1, v[0:1]
	v_or_b32_e32 v0, 0x400, v122
	v_add_u32_e32 v124, 0x4400, v122
	v_readfirstlane_b32 s16, v0
	v_and_b32_e32 v17, 56, v3
	v_lshl_add_u64 v[6:7], s[12:13], 0, v[4:5]
	s_mov_b32 m0, s16
	v_readfirstlane_b32 s16, v124
	v_mov_b32_e32 v3, v1
	v_or_b32_e32 v0, 0x800, v122
	global_load_lds_dwordx4 v[6:7], off
	v_lshl_add_u64 v[6:7], s[14:15], 0, v[4:5]
	s_mov_b32 m0, s16
	v_lshlrev_b64 v[2:3], 1, v[2:3]
	v_readfirstlane_b32 s16, v0
	v_add_u32_e32 v125, 0x4800, v122
	global_load_lds_dwordx4 v[6:7], off
	v_lshl_add_u64 v[6:7], s[12:13], 0, v[2:3]
	s_mov_b32 m0, s16
	v_readfirstlane_b32 s16, v125
	global_load_lds_dwordx4 v[6:7], off
	s_mov_b32 m0, s16
	v_readlane_b32 s16, v255, 35
	v_readlane_b32 s17, v255, 36
	s_movk_i32 s17, 0xfc00
	v_lshl_add_u64 v[2:3], s[14:15], 0, v[2:3]
	v_and_or_b32 v0, v16, s17, v17
	global_load_lds_dwordx4 v[2:3], off
	v_lshlrev_b64 v[2:3], 1, v[0:1]
	v_or_b32_e32 v0, 0xc00, v122
	v_lshl_add_u64 v[6:7], s[12:13], 0, v[2:3]
	v_readfirstlane_b32 s12, v0
	v_add_u32_e32 v126, 0x4c00, v122
	s_mov_b32 m0, s12
	v_readfirstlane_b32 s12, v126
	global_load_lds_dwordx4 v[6:7], off
	v_lshl_add_u64 v[6:7], s[14:15], 0, v[2:3]
	s_mov_b32 m0, s12
	v_lshrrev_b32_e32 v0, 1, v8
	global_load_lds_dwordx4 v[6:7], off
	v_ashrrev_i32_e32 v10, 7, v8
	v_bitop3_b32 v0, v12, v0, 7 bitop3:0x78
	v_lshlrev_b32_e32 v16, 13, v11
	v_bfe_u32 v6, v8, 1, 3
	v_lshlrev_b32_e32 v0, 4, v0
	v_lshlrev_b32_e32 v7, 13, v10
	v_and_b32_e32 v16, 0x2000, v16
	v_or_b32_e32 v15, v0, v7
	v_or_b32_e32 v17, v0, v16
	v_bitop3_b32 v0, v12, v6, 4 bitop3:0x36
	v_lshlrev_b32_e32 v6, 3, v8
	v_lshlrev_b32_e32 v0, 4, v0
	v_and_b32_e32 v6, 0x78, v6
	v_or_b32_e32 v12, v0, v7
	v_add_u32_e32 v7, 0x100, v8
	s_waitcnt vmcnt(0)
	v_lshlrev_b32_e32 v24, 7, v6
	v_or_b32_e32 v27, 2, v6
	v_or_b32_e32 v30, 3, v6
	v_or_b32_e32 v33, 4, v6
	v_or_b32_e32 v36, 5, v6
	v_or_b32_e32 v39, 6, v6
	v_or_b32_e32 v6, 7, v6
	v_ashrrev_i32_e32 v18, 4, v7
	v_lshlrev_b32_e32 v25, 2, v8
	v_lshlrev_b32_e32 v28, 7, v27
	v_lshrrev_b32_e32 v27, 1, v27
	v_lshlrev_b32_e32 v31, 7, v30
	v_lshrrev_b32_e32 v30, 1, v30
	v_lshlrev_b32_e32 v34, 7, v33
	v_lshrrev_b32_e32 v33, 1, v33
	v_lshlrev_b32_e32 v37, 7, v36
	v_lshrrev_b32_e32 v36, 1, v36
	v_lshlrev_b32_e32 v40, 7, v39
	v_lshrrev_b32_e32 v39, 1, v39
	v_lshlrev_b32_e32 v42, 7, v6
	v_lshrrev_b32_e32 v6, 1, v6
	v_ashrrev_i32_e32 v7, 7, v7
	v_add_u32_e32 v19, 0x200, v8
	v_bitop3_b32 v43, v25, v7, 4 bitop3:0x6c
	v_bitop3_b32 v44, v27, v7, 5 bitop3:0x6c
	v_bitop3_b32 v45, v30, v7, 5 bitop3:0x6c
	v_bitop3_b32 v46, v33, v7, 6 bitop3:0x6c
	v_bitop3_b32 v47, v36, v7, 6 bitop3:0x6c
	v_bitop3_b32 v48, v39, v7, 7 bitop3:0x6c
	v_bitop3_b32 v7, v6, v7, 7 bitop3:0x6c
	v_lshl_add_u32 v49, v7, 4, v42
	v_ashrrev_i32_e32 v7, 7, v19
	v_ashrrev_i32_e32 v20, 4, v19
	v_add_u32_e32 v21, 0x300, v8
	v_bitop3_b32 v19, v25, v7, 4 bitop3:0x6c
	v_bitop3_b32 v50, v27, v7, 5 bitop3:0x6c
	v_bitop3_b32 v51, v30, v7, 5 bitop3:0x6c
	v_bitop3_b32 v52, v33, v7, 6 bitop3:0x6c
	v_bitop3_b32 v53, v36, v7, 6 bitop3:0x6c
	v_bitop3_b32 v54, v39, v7, 7 bitop3:0x6c
	v_bitop3_b32 v7, v6, v7, 7 bitop3:0x6c
	v_lshl_add_u32 v55, v7, 4, v42
	v_ashrrev_i32_e32 v7, 7, v21
	v_ashrrev_i32_e32 v22, 4, v21
	v_bitop3_b32 v26, v25, v10, 4 bitop3:0x6c
	v_bitop3_b32 v21, v25, v7, 4 bitop3:0x6c
	v_lshlrev_b32_e32 v14, 7, v8
	v_or_b32_e32 v16, v0, v16
	v_ashrrev_i32_e32 v0, 4, v8
	v_lshrrev_b32_e32 v23, 3, v8
	v_lshl_add_u32 v26, v26, 4, v24
	v_bitop3_b32 v29, v27, v10, 5 bitop3:0x6c
	v_bitop3_b32 v32, v30, v10, 5 bitop3:0x6c
	v_bitop3_b32 v35, v33, v10, 6 bitop3:0x6c
	v_bitop3_b32 v38, v36, v10, 6 bitop3:0x6c
	v_bitop3_b32 v41, v39, v10, 7 bitop3:0x6c
	v_bitop3_b32 v10, v6, v10, 7 bitop3:0x6c
	v_lshl_add_u32 v43, v43, 4, v24
	v_lshl_add_u32 v19, v19, 4, v24
	v_lshl_add_u32 v21, v21, 4, v24
	v_bitop3_b32 v24, v27, v7, 5 bitop3:0x6c
	v_bitop3_b32 v25, v30, v7, 5 bitop3:0x6c
	v_bitop3_b32 v6, v6, v7, 7 bitop3:0x6c
	s_mov_b32 s14, 0xc000
	v_lshlrev_b32_e32 v8, 4, v8
	v_lshl_add_u32 v29, v29, 4, v28
	v_lshl_add_u32 v32, v32, 4, v31
	v_lshl_add_u32 v44, v44, 4, v28
	v_lshl_add_u32 v45, v45, 4, v31
	v_lshl_add_u32 v50, v50, 4, v28
	v_lshl_add_u32 v51, v51, 4, v31
	v_lshl_add_u32 v24, v24, 4, v28
	v_lshl_add_u32 v25, v25, 4, v31
	v_bitop3_b32 v27, v33, v7, 6 bitop3:0x6c
	v_bitop3_b32 v28, v36, v7, 6 bitop3:0x6c
	v_bitop3_b32 v30, v39, v7, 7 bitop3:0x6c
	v_lshl_add_u32 v31, v6, 4, v42
	v_mad_i64_i32 v[6:7], s[12:13], v22, s14, 0
	v_and_b32_e32 v8, 0xf0, v8
	v_or_b32_e32 v6, v6, v8
	v_lshl_add_u64 v[82:83], v[6:7], 0, s[40:41]
	v_mad_i64_i32 v[6:7], s[12:13], v20, s14, 0
	v_or_b32_e32 v6, v6, v8
	v_lshl_add_u64 v[84:85], v[6:7], 0, s[40:41]
	v_mad_i64_i32 v[6:7], s[12:13], v18, s14, 0
	v_or_b32_e32 v6, v6, v8
	v_lshl_add_u64 v[86:87], v[6:7], 0, s[40:41]
	v_mad_i64_i32 v[6:7], s[12:13], v0, s14, 0
	v_lshlrev_b32_e32 v0, 7, v9
	v_or_b32_e32 v6, v6, v8
	v_lshl_or_b32 v0, v11, 15, v0
	v_lshl_add_u64 v[88:89], v[6:7], 0, s[40:41]
	v_and_or_b32 v6, v0, s42, v13
	s_waitcnt vmcnt(0)
	s_add_u32 s12, s0, s11
	v_or_b32_e32 v0, 0x4000, v6
	v_mov_b32_e32 v7, v1
	v_and_b32_e32 v14, 0x780, v14
	v_and_b32_e32 v23, 14, v23
	v_lshl_add_u32 v35, v35, 4, v34
	v_lshl_add_u32 v38, v38, 4, v37
	v_lshl_add_u32 v41, v41, 4, v40
	v_lshl_add_u32 v10, v10, 4, v42
	v_lshl_add_u32 v46, v46, 4, v34
	v_lshl_add_u32 v47, v47, 4, v37
	v_lshl_add_u32 v48, v48, 4, v40
	v_lshl_add_u32 v52, v52, 4, v34
	v_lshl_add_u32 v53, v53, 4, v37
	v_lshl_add_u32 v54, v54, 4, v40
	v_lshl_add_u32 v27, v27, 4, v34
	v_lshl_add_u32 v28, v28, 4, v37
	v_lshl_add_u32 v30, v30, 4, v40
	s_addc_u32 s13, s1, 0
	v_lshlrev_b64 v[8:9], 1, v[0:1]
	v_lshlrev_b64 v[6:7], 1, v[6:7]
	v_mov_b32_e32 v18, 0
	v_lshl_add_u64 v[90:91], s[12:13], 0, v[2:3]
	v_lshl_add_u64 v[92:93], s[12:13], 0, v[8:9]
	v_lshl_add_u64 v[94:95], s[12:13], 0, v[4:5]
	v_lshl_add_u64 v[96:97], s[12:13], 0, v[6:7]
	v_lshl_add_u64 v[98:99], s[38:39], 0, v[4:5]
	v_lshl_add_u64 v[100:101], s[38:39], 0, v[6:7]
	v_lshl_add_u64 v[102:103], s[38:39], 0, v[8:9]
	v_lshl_add_u64 v[104:105], s[38:39], 0, v[2:3]
	s_mov_b32 s11, 0
	v_add_u32_e32 v0, v15, v14
	v_add_u32_e32 v127, v17, v14
	v_add_u32_e32 v128, v12, v14
	v_add_u32_e32 v129, v16, v14
	v_add_u32_e32 v130, v26, v23
	v_add_u32_e32 v131, v29, v23
	v_add_u32_e32 v132, v32, v23
	v_add_u32_e32 v133, v35, v23
	v_add_u32_e32 v134, v38, v23
	v_add_u32_e32 v135, v41, v23
	v_add_u32_e32 v136, v10, v23
	v_add_u32_e32 v137, v43, v23
	v_add_u32_e32 v138, v44, v23
	v_add_u32_e32 v139, v45, v23
	v_add_u32_e32 v140, v46, v23
	v_add_u32_e32 v141, v47, v23
	v_add_u32_e32 v142, v48, v23
	v_add_u32_e32 v143, v49, v23
	v_add_u32_e32 v144, v19, v23
	v_add_u32_e32 v145, v50, v23
	v_add_u32_e32 v154, v51, v23
	v_add_u32_e32 v155, v52, v23
	v_add_u32_e32 v156, v53, v23
	v_add_u32_e32 v157, v54, v23
	v_add_u32_e32 v158, v55, v23
	v_add_u32_e32 v159, v21, v23
	v_add_u32_e32 v160, v24, v23
	v_add_u32_e32 v161, v25, v23
	v_add_u32_e32 v162, v27, v23
	v_add_u32_e32 v163, v28, v23
	v_add_u32_e32 v164, v30, v23
	v_add_u32_e32 v165, v31, v23
	v_and_b32_e32 v240, 15, v151
	v_lshrrev_b32_e32 v241, 4, v151
	v_sub_u32_e32 v242, v240, v241
	v_mul_i32_i24_e32 v244, 0xbff0, v242
	v_ashrrev_i32_e32 v245, 31, v244
	v_lshl_add_u64 v[82:83], v[82:83], 0, v[244:245]
	v_lshl_add_u64 v[84:85], v[84:85], 0, v[244:245]
	v_lshl_add_u64 v[86:87], v[86:87], 0, v[244:245]
	v_lshl_add_u64 v[88:89], v[88:89], 0, v[244:245]
	v_and_b32_e32 v246, 7, v240
	v_lshlrev_b32_e32 v246, 1, v246
	v_lshl_or_b32 v246, v241, 10, v246
	v_lshrrev_b32_e32 v247, 3, v240
	v_and_b32_e32 v242, 1, v241
	v_lshlrev_b32_e32 v242, 2, v242
	v_add_u32_e32 v243, 0, v247
	v_or_b32_e32 v248, 0, v242
	v_xor_b32_e32 v248, v243, v248
	v_lshl_add_u32 v130, v248, 4, v246
	v_or_b32_e32 v248, 1, v242
	v_xor_b32_e32 v248, v243, v248
	v_lshl_add_u32 v248, v248, 4, v246
	v_add_u32_e32 v131, 0x100, v248
	v_add_u32_e32 v132, 0x180, v248
	v_or_b32_e32 v248, 2, v242
	v_xor_b32_e32 v248, v243, v248
	v_lshl_add_u32 v248, v248, 4, v246
	v_add_u32_e32 v133, 0x200, v248
	v_add_u32_e32 v134, 0x280, v248
	v_or_b32_e32 v248, 3, v242
	v_xor_b32_e32 v248, v243, v248
	v_lshl_add_u32 v248, v248, 4, v246
	v_add_u32_e32 v135, 0x300, v248
	v_add_u32_e32 v136, 0x380, v248
	v_add_u32_e32 v243, 2, v247
	v_or_b32_e32 v248, 0, v242
	v_xor_b32_e32 v248, v243, v248
	v_lshl_add_u32 v137, v248, 4, v246
	v_or_b32_e32 v248, 1, v242
	v_xor_b32_e32 v248, v243, v248
	v_lshl_add_u32 v248, v248, 4, v246
	v_add_u32_e32 v138, 0x100, v248
	v_add_u32_e32 v139, 0x180, v248
	v_or_b32_e32 v248, 2, v242
	v_xor_b32_e32 v248, v243, v248
	v_lshl_add_u32 v248, v248, 4, v246
	v_add_u32_e32 v140, 0x200, v248
	v_add_u32_e32 v141, 0x280, v248
	v_or_b32_e32 v248, 3, v242
	v_xor_b32_e32 v248, v243, v248
	v_lshl_add_u32 v248, v248, 4, v246
	v_add_u32_e32 v142, 0x300, v248
	v_add_u32_e32 v143, 0x380, v248
	v_add_u32_e32 v243, 4, v247
	v_or_b32_e32 v248, 0, v242
	v_xor_b32_e32 v248, v243, v248
	v_lshl_add_u32 v144, v248, 4, v246
	v_or_b32_e32 v248, 1, v242
	v_xor_b32_e32 v248, v243, v248
	v_lshl_add_u32 v248, v248, 4, v246
	v_add_u32_e32 v145, 0x100, v248
	v_add_u32_e32 v154, 0x180, v248
	v_or_b32_e32 v248, 2, v242
	v_xor_b32_e32 v248, v243, v248
	v_lshl_add_u32 v248, v248, 4, v246
	v_add_u32_e32 v155, 0x200, v248
	v_add_u32_e32 v156, 0x280, v248
	v_or_b32_e32 v248, 3, v242
	v_xor_b32_e32 v248, v243, v248
	v_lshl_add_u32 v248, v248, 4, v246
	v_add_u32_e32 v157, 0x300, v248
	v_add_u32_e32 v158, 0x380, v248
	v_add_u32_e32 v243, 6, v247
	v_or_b32_e32 v248, 0, v242
	v_xor_b32_e32 v248, v243, v248
	v_lshl_add_u32 v159, v248, 4, v246
	v_or_b32_e32 v248, 1, v242
	v_xor_b32_e32 v248, v243, v248
	v_lshl_add_u32 v248, v248, 4, v246
	v_add_u32_e32 v160, 0x100, v248
	v_add_u32_e32 v161, 0x180, v248
	v_or_b32_e32 v248, 2, v242
	v_xor_b32_e32 v248, v243, v248
	v_lshl_add_u32 v248, v248, 4, v246
	v_add_u32_e32 v162, 0x200, v248
	v_add_u32_e32 v163, 0x280, v248
	v_or_b32_e32 v248, 3, v242
	v_xor_b32_e32 v248, v243, v248
	v_lshl_add_u32 v248, v248, 4, v246
	v_add_u32_e32 v164, 0x300, v248
	v_add_u32_e32 v165, 0x380, v248
	v_mov_b32_e32 v19, v18
	v_mov_b32_e32 v20, v18
	v_mov_b32_e32 v21, v18
	v_mov_b32_e32 v22, v18
	v_mov_b32_e32 v23, v18
	v_mov_b32_e32 v24, v18
	v_mov_b32_e32 v25, v18
	v_mov_b32_e32 v26, v18
	v_mov_b32_e32 v27, v18
	v_mov_b32_e32 v28, v18
	v_mov_b32_e32 v29, v18
	v_mov_b32_e32 v30, v18
	v_mov_b32_e32 v31, v18
	v_mov_b32_e32 v32, v18
	v_mov_b32_e32 v33, v18
	v_mov_b32_e32 v34, v18
	v_mov_b32_e32 v35, v18
	v_mov_b32_e32 v36, v18
	v_mov_b32_e32 v37, v18
	v_mov_b32_e32 v38, v18
	v_mov_b32_e32 v39, v18
	v_mov_b32_e32 v40, v18
	v_mov_b32_e32 v41, v18
	v_mov_b32_e32 v42, v18
	v_mov_b32_e32 v43, v18
	v_mov_b32_e32 v44, v18
	v_mov_b32_e32 v45, v18
	v_mov_b32_e32 v46, v18
	v_mov_b32_e32 v47, v18
	v_mov_b32_e32 v48, v18
	v_mov_b32_e32 v49, v18
	v_mov_b32_e32 v50, v18
	v_mov_b32_e32 v51, v18
	v_mov_b32_e32 v52, v18
	v_mov_b32_e32 v53, v18
	v_mov_b32_e32 v54, v18
	v_mov_b32_e32 v55, v18
	v_mov_b32_e32 v56, v18
	v_mov_b32_e32 v57, v18
	v_mov_b32_e32 v58, v18
	v_mov_b32_e32 v59, v18
	v_mov_b32_e32 v60, v18
	v_mov_b32_e32 v61, v18
	v_mov_b32_e32 v62, v18
	v_mov_b32_e32 v63, v18
	v_mov_b32_e32 v64, v18
	v_mov_b32_e32 v65, v18
	v_mov_b32_e32 v66, v18
	v_mov_b32_e32 v67, v18
	v_mov_b32_e32 v68, v18
	v_mov_b32_e32 v69, v18
	v_mov_b32_e32 v70, v18
	v_mov_b32_e32 v71, v18
	v_mov_b32_e32 v72, v18
	v_mov_b32_e32 v73, v18
	v_mov_b32_e32 v74, v18
	v_mov_b32_e32 v75, v18
	v_mov_b32_e32 v76, v18
	v_mov_b32_e32 v77, v18
	v_mov_b32_e32 v78, v18
	v_mov_b32_e32 v79, v18
	v_mov_b32_e32 v80, v18
	v_mov_b32_e32 v81, v18
	s_mov_b32 s13, 0x7b00000
	s_mov_b32 s17, 0x7e00000
	v_readfirstlane_b32 s12, v122
	s_mov_b64 s[38:39], 0
	s_mov_b64 s[40:41], -1
	s_cmp_eq_u32 s13, s13
	s_waitcnt lgkmcnt(0)
	s_barrier
	s_branch .LBB0_76
.LBB0_75:
	s_waitcnt vmcnt(0)
	v_lshl_add_u64 v[82:83], v[82:83], 0, s[20:21]
	v_lshl_add_u64 v[84:85], v[84:85], 0, s[20:21]
	v_lshl_add_u64 v[86:87], v[86:87], 0, s[20:21]
	v_lshl_add_u64 v[88:89], v[88:89], 0, s[20:21]
	s_andn2_b64 vcc, exec, s[38:39]
	s_mov_b32 s11, s12
	v_readfirstlane_b32 s12, v122
	s_and_b32 s40, s11, 12
	s_cmp_eq_u32 s40, 8
	s_cselect_b64 s[38:39], -1, 0
	s_cmp_lg_u32 s40, 8
	s_mov_b64 s[40:41], -1
	s_waitcnt vmcnt(0) lgkmcnt(0)
	s_barrier
	s_cbranch_vccz .LBB0_73
.LBB0_76:
	s_cbranch_scc0 .LBB0_78
	s_add_u32 m0, s12, 0x9000
	s_nop 0
	global_load_lds_dwordx4 v185, s[48:49]
	s_add_u32 m0, s12, 0xd000
	s_nop 0
	global_load_lds_dwordx4 v185, s[100:101]
	s_add_u32 m0, s12, 0x9400
	s_nop 0
	global_load_lds_dwordx4 v188, s[48:49]
	s_add_u32 m0, s12, 0xd400
	s_nop 0
	global_load_lds_dwordx4 v188, s[100:101]
	s_add_u32 m0, s12, 0x9800
	s_nop 0
	global_load_lds_dwordx4 v193, s[48:49]
	s_add_u32 m0, s12, 0xd800
	s_nop 0
	global_load_lds_dwordx4 v193, s[100:101]
	s_add_u32 m0, s12, 0x9c00
	s_nop 0
	global_load_lds_dwordx4 v194, s[48:49]
	s_add_u32 m0, s12, 0xdc00
	s_nop 0
	global_load_lds_dwordx4 v194, s[100:101]
	v_add_u32_e32 v185, 0x80, v185
	v_add_u32_e32 v188, 0x80, v188
	v_add_u32_e32 v193, 0x80, v193
	v_add_u32_e32 v194, 0x80, v194
	s_mov_b64 s[40:41], 0
.LBB0_78:
	s_andn2_b64 vcc, exec, s[40:41]
	s_cbranch_vccnz .LBB0_80
	s_add_u32 m0, s12, 0xd000
	s_nop 0
	global_load_lds_dwordx4 v185, s[100:101]
	s_add_u32 m0, s12, 0xd400
	s_nop 0
	global_load_lds_dwordx4 v188, s[100:101]
	s_add_u32 m0, s12, 0xd800
	s_nop 0
	global_load_lds_dwordx4 v193, s[100:101]
	s_add_u32 m0, s12, 0xdc00
	s_nop 0
	global_load_lds_dwordx4 v194, s[100:101]
	v_add_u32_e32 v185, 0x80, v185
	v_add_u32_e32 v188, 0x80, v188
	v_add_u32_e32 v193, 0x80, v193
	v_add_u32_e32 v194, 0x80, v194
	v_lshl_add_u64 v[2:3], s[94:95], 0, v[88:89]
	v_add_co_u32_e32 v2, vcc, s13, v2
	v_lshl_add_u64 v[4:5], s[94:95], 0, v[86:87]
	s_nop 0
	v_addc_co_u32_e32 v3, vcc, 0, v3, vcc
	v_add_co_u32_e32 v6, vcc, s13, v4
	v_addc_co_u32_e32 v7, vcc, 0, v5, vcc
	v_lshl_add_u64 v[10:11], s[94:95], 0, v[84:85]
	v_add_co_u32_e32 v10, vcc, 0x7b00000, v10
	v_addc_co_u32_e32 v11, vcc, 0, v11, vcc
	v_lshl_add_u64 v[12:13], s[94:95], 0, v[82:83]
	v_add_co_u32_e32 v14, vcc, 0x7b00000, v12
	s_nop 0
	v_addc_co_u32_e32 v15, vcc, 0, v13, vcc
	global_load_dwordx4 v[2:5], v[2:3], off
	s_nop 0
	global_load_dwordx4 v[6:9], v[6:7], off
	s_nop 0
	global_load_dwordx4 v[10:13], v[10:11], off
	s_nop 0
	global_load_dwordx4 v[14:17], v[14:15], off

.LBB0_82:
	s_add_i32 s12, s11, 2
	s_waitcnt vmcnt(0)
	s_cmp_gt_u32 s11, 13
	s_cselect_b64 s[38:39], -1, 0
	s_mov_b64 s[40:41], 0
	s_and_b64 vcc, exec, s[38:39]
	s_and_b32 s11, s12, 28
	s_cmp_lg_u32 s11, 8
	v_readfirstlane_b32 s11, v122
	s_waitcnt vmcnt(0) lgkmcnt(0)
	s_barrier
	s_cbranch_vccnz .LBB0_87
	s_mov_b64 s[14:15], 0xe600100
	s_mov_b64 s[40:41], -1
	s_cbranch_scc0 .LBB0_85
	s_add_u32 m0, s11, 0x0
	s_nop 0
	global_load_lds_dwordx4 v185, s[48:49]
	s_add_u32 m0, s11, 0x4000
	s_nop 0
	global_load_lds_dwordx4 v185, s[100:101]
	s_add_u32 m0, s11, 0x400
	s_nop 0
	global_load_lds_dwordx4 v188, s[48:49]
	s_add_u32 m0, s11, 0x4400
	s_nop 0
	global_load_lds_dwordx4 v188, s[100:101]
	s_add_u32 m0, s11, 0x800
	s_nop 0
	global_load_lds_dwordx4 v193, s[48:49]
	s_add_u32 m0, s11, 0x4800
	s_nop 0
	global_load_lds_dwordx4 v193, s[100:101]
	s_add_u32 m0, s11, 0xc00
	s_nop 0
	global_load_lds_dwordx4 v194, s[48:49]
	s_add_u32 m0, s11, 0x4c00
	s_nop 0
	global_load_lds_dwordx4 v194, s[100:101]
	v_add_u32_e32 v185, 0x80, v185
	v_add_u32_e32 v188, 0x80, v188
	v_add_u32_e32 v193, 0x80, v193
	v_add_u32_e32 v194, 0x80, v194
	s_mov_b64 s[40:41], 0
.LBB0_85:
	s_andn2_b64 vcc, exec, s[40:41]
	s_mov_b64 s[40:41], 0
	s_cbranch_vccnz .LBB0_87
	s_add_u32 m0, s11, 0x4000
	s_nop 0
	global_load_lds_dwordx4 v185, s[100:101]
	s_add_u32 m0, s11, 0x4400
	s_nop 0
	global_load_lds_dwordx4 v188, s[100:101]
	s_add_u32 m0, s11, 0x4800
	s_nop 0
	global_load_lds_dwordx4 v193, s[100:101]
	s_add_u32 m0, s11, 0x4c00
	s_nop 0
	global_load_lds_dwordx4 v194, s[100:101]
	v_add_u32_e32 v185, 0x80, v185
	v_add_u32_e32 v188, 0x80, v188
	v_add_u32_e32 v193, 0x80, v193
	v_add_u32_e32 v194, 0x80, v194
	v_lshl_add_u64 v[2:3], s[94:95], 0, v[88:89]
	v_add_co_u32_e32 v2, vcc, s17, v2
	v_lshl_add_u64 v[4:5], s[94:95], 0, v[86:87]
	s_nop 0
	v_addc_co_u32_e32 v3, vcc, 0, v3, vcc
	v_add_co_u32_e32 v6, vcc, s17, v4
	v_addc_co_u32_e32 v7, vcc, 0, v5, vcc
	v_lshl_add_u64 v[10:11], s[94:95], 0, v[84:85]
	v_add_co_u32_e32 v10, vcc, 0x7e00000, v10
	v_addc_co_u32_e32 v11, vcc, 0, v11, vcc
	v_lshl_add_u64 v[12:13], s[94:95], 0, v[82:83]
	v_add_co_u32_e32 v14, vcc, 0x7e00000, v12
	s_nop 0
	v_addc_co_u32_e32 v15, vcc, 0, v13, vcc
	global_load_dwordx4 v[2:5], v[2:3], off
	s_nop 0
	global_load_dwordx4 v[6:9], v[6:7], off
	s_nop 0
	global_load_dwordx4 v[10:13], v[10:11], off
	s_nop 0
	global_load_dwordx4 v[14:17], v[14:15], off
	s_mov_b64 s[40:41], -1
